# final epilogue: workgroup's final_g slice staged in LDS, row sums loaded together; output stores no longer serialized behind per-store waits
# speedup vs baseline: 1.0209x; 1.0056x over previous
.LBB0_2175:
	s_cmp_lt_i32 s94, 15
	s_cselect_b64 s[6:7], -1, 0
	s_and_b32 s2, s80, 63
	s_cmp_lg_u32 s2, 0
	s_cselect_b64 s[4:5], -1, 0
	s_cmp_eq_u32 s2, 0
	s_cselect_b64 s[2:3], -1, 0
	s_and_b64 s[6:7], s[6:7], s[0:1]
	s_andn2_b64 vcc, exec, s[6:7]
	s_cbranch_vccnz .LBB0_2263
	s_andn2_b64 vcc, exec, s[2:3]
	s_mov_b64 s[0:1], -1
	s_cbranch_vccnz .LBB0_2224
	s_lshr_b32 s98, s25, 3
	s_and_b32 s98, s98, 7
	s_lshl_b32 s98, s98, 10
	v_and_b32_e32 v230, 0xff, v174
	v_lshlrev_b32_e32 v230, 2, v230
	v_add_u32_e32 v231, s98, v230
	global_load_dword v231, v231, s[88:89]
	v_add_u32_e32 v230, 0x22000, v230
	s_waitcnt vmcnt(0)
	ds_write_b32 v230, v231
	s_waitcnt lgkmcnt(0)
	s_ashr_i32 s0, s25, 31
	s_lshr_b32 s1, s0, 29
	s_add_i32 s12, s25, s1
	s_and_b32 s1, s12, -8
	s_lshr_b32 s0, s0, 26
	s_sub_i32 s1, s25, s1
	s_ashr_i32 s2, s80, 6
	s_add_i32 s0, s25, s0
	s_mul_i32 s35, s2, s1
	s_ashr_i32 s0, s0, 6
	s_add_i32 s35, s35, s0
	s_cmpk_lt_i32 s35, 0x60
	s_cselect_b64 s[0:1], -1, 0
	s_cmpk_gt_i32 s35, 0x5f
	v_readfirstlane_b32 s13, v174
	s_cbranch_scc1 .LBB0_2179
	s_ashr_i32 s2, s12, 3
	s_lshr_b32 s3, s2, 29
	s_add_i32 s3, s2, s3
	s_and_b32 s3, s3, -8
	s_sub_i32 s61, s2, s3

.LBB0_2211:
	s_waitcnt vmcnt(0) lgkmcnt(0)
	s_barrier
	global_load_dword v230, v[112:113], off sc1
	global_load_dword v231, v[112:113], off offset:64 sc1
	global_load_dword v232, v[112:113], off offset:128 sc1
	global_load_dword v233, v[112:113], off offset:192 sc1
	global_load_dword v234, v[112:113], off offset:512 sc1
	global_load_dword v235, v[112:113], off offset:576 sc1
	global_load_dword v236, v[112:113], off offset:640 sc1
	global_load_dword v237, v[112:113], off offset:704 sc1
	s_waitcnt vmcnt(0)
	v_and_b32_e32 v238, 0xff, v142
	v_lshlrev_b32_e32 v238, 2, v238
	v_add_u32_e32 v238, 0x22000, v238
	v_lshl_add_u64 v[142:143], v[142:143], 2, s[88:89]
	s_waitcnt lgkmcnt(0)
	ds_read_b128 v[160:163], v238
	s_andn2_b64 vcc, exec, s[24:25]
	s_mov_b64 s[24:25], -1
	v_fmamk_f32 v164, v230, 0x3a000000, v189
	v_rsq_f32_e32 v164, v164
	s_nop 0
	v_pk_mul_f32 v[166:167], v[146:147], v[164:165] op_sel_hi:[1,0]
	v_pk_mul_f32 v[144:145], v[144:145], v[164:165] op_sel_hi:[1,0]
	s_waitcnt lgkmcnt(0)
	v_pk_mul_f32 v[146:147], v[162:163], v[144:145]
	v_pk_mul_f32 v[144:145], v[160:161], v[166:167]
	global_store_dwordx4 v[140:141], v[144:147], off
	ds_read_b128 v[144:147], v238 offset:16
	v_pk_mul_f32 v[160:161], v[124:125], v[164:165] op_sel_hi:[1,0]
	v_pk_mul_f32 v[124:125], v[126:127], v[164:165] op_sel_hi:[1,0]
	s_waitcnt lgkmcnt(0)
	v_pk_mul_f32 v[126:127], v[146:147], v[160:161]
	v_pk_mul_f32 v[124:125], v[144:145], v[124:125]
	global_store_dwordx4 v[140:141], v[124:127], off offset:16
	ds_read_b128 v[124:127], v238 offset:512
	v_pk_mul_f32 v[144:145], v[120:121], v[164:165] op_sel_hi:[1,0]
	v_pk_mul_f32 v[120:121], v[122:123], v[164:165] op_sel_hi:[1,0]
	s_waitcnt lgkmcnt(0)
	v_pk_mul_f32 v[122:123], v[126:127], v[144:145]
	v_pk_mul_f32 v[120:121], v[124:125], v[120:121]
	global_store_dwordx4 v[140:141], v[120:123], off offset:512
	ds_read_b128 v[120:123], v238 offset:528
	v_pk_mul_f32 v[124:125], v[116:117], v[164:165] op_sel_hi:[1,0]
	v_pk_mul_f32 v[116:117], v[118:119], v[164:165] op_sel_hi:[1,0]
	s_waitcnt lgkmcnt(0)
	v_pk_mul_f32 v[118:119], v[124:125], v[122:123]
	v_pk_mul_f32 v[116:117], v[116:117], v[120:121]
	global_store_dwordx4 v[140:141], v[116:119], off offset:528
	s_nop 0
	ds_read_b128 v[116:119], v238
	v_fmamk_f32 v120, v231, 0x3a000000, v189
	v_rsq_f32_e32 v120, v120
	s_nop 0
	v_pk_mul_f32 v[122:123], v[148:149], v[120:121] op_sel_hi:[1,0]
	v_pk_mul_f32 v[110:111], v[110:111], v[120:121] op_sel_hi:[1,0]
	s_waitcnt lgkmcnt(0)
	v_pk_mul_f32 v[116:117], v[116:117], v[122:123]
	v_pk_mul_f32 v[118:119], v[118:119], v[110:111]
	global_store_dwordx4 v[114:115], v[116:119], off
	ds_read_b128 v[116:119], v238 offset:16
	v_pk_mul_f32 v[110:111], v[106:107], v[120:121] op_sel_hi:[1,0]
	v_pk_mul_f32 v[106:107], v[108:109], v[120:121] op_sel_hi:[1,0]
	s_waitcnt lgkmcnt(0)
	v_pk_mul_f32 v[108:109], v[118:119], v[110:111]
	v_pk_mul_f32 v[106:107], v[116:117], v[106:107]
	global_store_dwordx4 v[114:115], v[106:109], off offset:16
	ds_read_b128 v[106:109], v238 offset:512
	v_pk_mul_f32 v[110:111], v[102:103], v[120:121] op_sel_hi:[1,0]
	v_pk_mul_f32 v[102:103], v[104:105], v[120:121] op_sel_hi:[1,0]
	s_waitcnt lgkmcnt(0)
	v_pk_mul_f32 v[104:105], v[108:109], v[110:111]
	v_pk_mul_f32 v[102:103], v[106:107], v[102:103]
	global_store_dwordx4 v[114:115], v[102:105], off offset:512
	ds_read_b128 v[102:105], v238 offset:528
	v_pk_mul_f32 v[106:107], v[98:99], v[120:121] op_sel_hi:[1,0]
	v_pk_mul_f32 v[98:99], v[100:101], v[120:121] op_sel_hi:[1,0]
	s_waitcnt lgkmcnt(0)
	v_pk_mul_f32 v[100:101], v[106:107], v[104:105]
	v_pk_mul_f32 v[98:99], v[98:99], v[102:103]
	global_store_dwordx4 v[114:115], v[98:101], off offset:528
	s_nop 0
	ds_read_b128 v[98:101], v238
	v_fmamk_f32 v102, v232, 0x3a000000, v189
	v_rsq_f32_e32 v102, v102
	s_nop 0
	v_pk_mul_f32 v[104:105], v[150:151], v[102:103] op_sel_hi:[1,0]
	v_pk_mul_f32 v[94:95], v[94:95], v[102:103] op_sel_hi:[1,0]
	s_waitcnt lgkmcnt(0)
	v_pk_mul_f32 v[98:99], v[98:99], v[104:105]
	v_pk_mul_f32 v[100:101], v[100:101], v[94:95]
	global_store_dwordx4 v[96:97], v[98:101], off
	ds_read_b128 v[98:101], v238 offset:16
	v_pk_mul_f32 v[94:95], v[90:91], v[102:103] op_sel_hi:[1,0]
	v_pk_mul_f32 v[90:91], v[92:93], v[102:103] op_sel_hi:[1,0]
	s_waitcnt lgkmcnt(0)
	v_pk_mul_f32 v[92:93], v[100:101], v[94:95]
	v_pk_mul_f32 v[90:91], v[98:99], v[90:91]
	global_store_dwordx4 v[96:97], v[90:93], off offset:16
	ds_read_b128 v[90:93], v238 offset:512
	v_pk_mul_f32 v[94:95], v[86:87], v[102:103] op_sel_hi:[1,0]
	v_pk_mul_f32 v[86:87], v[88:89], v[102:103] op_sel_hi:[1,0]
	s_waitcnt lgkmcnt(0)
	v_pk_mul_f32 v[88:89], v[92:93], v[94:95]
	v_pk_mul_f32 v[86:87], v[90:91], v[86:87]
	global_store_dwordx4 v[96:97], v[86:89], off offset:512
	ds_read_b128 v[86:89], v238 offset:528
	v_pk_mul_f32 v[90:91], v[82:83], v[102:103] op_sel_hi:[1,0]
	v_pk_mul_f32 v[82:83], v[84:85], v[102:103] op_sel_hi:[1,0]
	s_waitcnt lgkmcnt(0)
	v_pk_mul_f32 v[84:85], v[90:91], v[88:89]
	v_pk_mul_f32 v[82:83], v[82:83], v[86:87]
	global_store_dwordx4 v[96:97], v[82:85], off offset:528
	s_nop 0
	ds_read_b128 v[82:85], v238
	v_fmamk_f32 v86, v233, 0x3a000000, v189
	v_rsq_f32_e32 v86, v86
	s_nop 0
	v_pk_mul_f32 v[88:89], v[152:153], v[86:87] op_sel_hi:[1,0]
	v_pk_mul_f32 v[78:79], v[78:79], v[86:87] op_sel_hi:[1,0]
	s_waitcnt lgkmcnt(0)
	v_pk_mul_f32 v[82:83], v[82:83], v[88:89]
	v_pk_mul_f32 v[84:85], v[84:85], v[78:79]
	global_store_dwordx4 v[80:81], v[82:85], off
	ds_read_b128 v[82:85], v238 offset:16
	v_pk_mul_f32 v[78:79], v[74:75], v[86:87] op_sel_hi:[1,0]
	v_pk_mul_f32 v[74:75], v[76:77], v[86:87] op_sel_hi:[1,0]
	s_waitcnt lgkmcnt(0)
	v_pk_mul_f32 v[76:77], v[84:85], v[78:79]
	v_pk_mul_f32 v[74:75], v[82:83], v[74:75]
	global_store_dwordx4 v[80:81], v[74:77], off offset:16
	ds_read_b128 v[74:77], v238 offset:512
	v_pk_mul_f32 v[78:79], v[70:71], v[86:87] op_sel_hi:[1,0]
	v_pk_mul_f32 v[70:71], v[72:73], v[86:87] op_sel_hi:[1,0]
	s_waitcnt lgkmcnt(0)
	v_pk_mul_f32 v[72:73], v[76:77], v[78:79]
	v_pk_mul_f32 v[70:71], v[74:75], v[70:71]
	global_store_dwordx4 v[80:81], v[70:73], off offset:512
	ds_read_b128 v[70:73], v238 offset:528
	v_pk_mul_f32 v[74:75], v[66:67], v[86:87] op_sel_hi:[1,0]
	v_pk_mul_f32 v[66:67], v[68:69], v[86:87] op_sel_hi:[1,0]
	s_waitcnt lgkmcnt(0)
	v_pk_mul_f32 v[68:69], v[74:75], v[72:73]
	v_pk_mul_f32 v[66:67], v[66:67], v[70:71]
	global_store_dwordx4 v[80:81], v[66:69], off offset:528
	s_nop 0
	ds_read_b128 v[66:69], v238
	v_fmamk_f32 v70, v234, 0x3a000000, v189
	v_rsq_f32_e32 v70, v70
	s_nop 0
	v_pk_mul_f32 v[72:73], v[154:155], v[70:71] op_sel_hi:[1,0]
	v_pk_mul_f32 v[62:63], v[62:63], v[70:71] op_sel_hi:[1,0]
	s_waitcnt lgkmcnt(0)
	v_pk_mul_f32 v[66:67], v[66:67], v[72:73]
	v_pk_mul_f32 v[68:69], v[68:69], v[62:63]
	global_store_dwordx4 v[64:65], v[66:69], off
	ds_read_b128 v[66:69], v238 offset:16
	v_pk_mul_f32 v[62:63], v[58:59], v[70:71] op_sel_hi:[1,0]
	v_pk_mul_f32 v[58:59], v[60:61], v[70:71] op_sel_hi:[1,0]
	s_waitcnt lgkmcnt(0)
	v_pk_mul_f32 v[60:61], v[68:69], v[62:63]
	v_pk_mul_f32 v[58:59], v[66:67], v[58:59]
	global_store_dwordx4 v[64:65], v[58:61], off offset:16
	ds_read_b128 v[58:61], v238 offset:512
	v_pk_mul_f32 v[62:63], v[54:55], v[70:71] op_sel_hi:[1,0]
	v_pk_mul_f32 v[54:55], v[56:57], v[70:71] op_sel_hi:[1,0]
	s_waitcnt lgkmcnt(0)
	v_pk_mul_f32 v[56:57], v[60:61], v[62:63]
	v_pk_mul_f32 v[54:55], v[58:59], v[54:55]
	global_store_dwordx4 v[64:65], v[54:57], off offset:512
	ds_read_b128 v[54:57], v238 offset:528
	v_pk_mul_f32 v[58:59], v[50:51], v[70:71] op_sel_hi:[1,0]
	v_pk_mul_f32 v[50:51], v[52:53], v[70:71] op_sel_hi:[1,0]
	s_waitcnt lgkmcnt(0)
	v_pk_mul_f32 v[52:53], v[58:59], v[56:57]
	v_pk_mul_f32 v[50:51], v[50:51], v[54:55]
	global_store_dwordx4 v[64:65], v[50:53], off offset:528
	s_nop 0
	ds_read_b128 v[50:53], v238
	v_fmamk_f32 v54, v235, 0x3a000000, v189
	v_rsq_f32_e32 v54, v54
	s_nop 0
	v_pk_mul_f32 v[56:57], v[156:157], v[54:55] op_sel_hi:[1,0]
	v_pk_mul_f32 v[46:47], v[46:47], v[54:55] op_sel_hi:[1,0]
	s_waitcnt lgkmcnt(0)
	v_pk_mul_f32 v[50:51], v[50:51], v[56:57]
	v_pk_mul_f32 v[52:53], v[52:53], v[46:47]
	global_store_dwordx4 v[48:49], v[50:53], off
	ds_read_b128 v[50:53], v238 offset:16
	v_pk_mul_f32 v[46:47], v[42:43], v[54:55] op_sel_hi:[1,0]
	v_pk_mul_f32 v[42:43], v[44:45], v[54:55] op_sel_hi:[1,0]
	s_waitcnt lgkmcnt(0)
	v_pk_mul_f32 v[44:45], v[52:53], v[46:47]
	v_pk_mul_f32 v[42:43], v[50:51], v[42:43]
	global_store_dwordx4 v[48:49], v[42:45], off offset:16
	ds_read_b128 v[42:45], v238 offset:512
	v_pk_mul_f32 v[46:47], v[38:39], v[54:55] op_sel_hi:[1,0]
	v_pk_mul_f32 v[38:39], v[40:41], v[54:55] op_sel_hi:[1,0]
	s_waitcnt lgkmcnt(0)
	v_pk_mul_f32 v[40:41], v[44:45], v[46:47]
	v_pk_mul_f32 v[38:39], v[42:43], v[38:39]
	global_store_dwordx4 v[48:49], v[38:41], off offset:512
	ds_read_b128 v[38:41], v238 offset:528
	v_pk_mul_f32 v[42:43], v[34:35], v[54:55] op_sel_hi:[1,0]
	v_pk_mul_f32 v[34:35], v[36:37], v[54:55] op_sel_hi:[1,0]
	s_waitcnt lgkmcnt(0)
	v_pk_mul_f32 v[36:37], v[42:43], v[40:41]
	v_pk_mul_f32 v[34:35], v[34:35], v[38:39]
	global_store_dwordx4 v[48:49], v[34:37], off offset:528
	s_nop 0
	ds_read_b128 v[34:37], v238
	v_fmamk_f32 v38, v236, 0x3a000000, v189
	v_rsq_f32_e32 v38, v38
	s_nop 0
	v_pk_mul_f32 v[40:41], v[158:159], v[38:39] op_sel_hi:[1,0]
	v_pk_mul_f32 v[30:31], v[30:31], v[38:39] op_sel_hi:[1,0]
	s_waitcnt lgkmcnt(0)
	v_pk_mul_f32 v[34:35], v[34:35], v[40:41]
	v_pk_mul_f32 v[36:37], v[36:37], v[30:31]
	global_store_dwordx4 v[32:33], v[34:37], off
	ds_read_b128 v[34:37], v238 offset:16
	v_pk_mul_f32 v[30:31], v[26:27], v[38:39] op_sel_hi:[1,0]
	v_pk_mul_f32 v[26:27], v[28:29], v[38:39] op_sel_hi:[1,0]
	s_waitcnt lgkmcnt(0)
	v_pk_mul_f32 v[28:29], v[36:37], v[30:31]
	v_pk_mul_f32 v[26:27], v[34:35], v[26:27]
	global_store_dwordx4 v[32:33], v[26:29], off offset:16
	ds_read_b128 v[26:29], v238 offset:512
	v_pk_mul_f32 v[30:31], v[22:23], v[38:39] op_sel_hi:[1,0]
	v_pk_mul_f32 v[22:23], v[24:25], v[38:39] op_sel_hi:[1,0]
	s_waitcnt lgkmcnt(0)
	v_pk_mul_f32 v[24:25], v[28:29], v[30:31]
	v_pk_mul_f32 v[22:23], v[26:27], v[22:23]
	global_store_dwordx4 v[32:33], v[22:25], off offset:512
	ds_read_b128 v[22:25], v238 offset:528
	v_pk_mul_f32 v[26:27], v[18:19], v[38:39] op_sel_hi:[1,0]
	v_pk_mul_f32 v[18:19], v[20:21], v[38:39] op_sel_hi:[1,0]
	s_waitcnt lgkmcnt(0)
	v_pk_mul_f32 v[20:21], v[26:27], v[24:25]
	v_pk_mul_f32 v[18:19], v[18:19], v[22:23]
	global_store_dwordx4 v[32:33], v[18:21], off offset:528
	s_nop 0
	ds_read_b128 v[18:21], v238
	v_fmamk_f32 v22, v237, 0x3a000000, v189
	v_rsq_f32_e32 v22, v22
	s_nop 0
	v_pk_mul_f32 v[12:13], v[12:13], v[22:23] op_sel_hi:[1,0]
	v_pk_mul_f32 v[14:15], v[14:15], v[22:23] op_sel_hi:[1,0]
	s_waitcnt lgkmcnt(0)
	v_pk_mul_f32 v[12:13], v[18:19], v[12:13]
	v_pk_mul_f32 v[14:15], v[20:21], v[14:15]
	global_store_dwordx4 v[16:17], v[12:15], off
	ds_read_b128 v[12:15], v238 offset:16
	v_pk_mul_f32 v[10:11], v[10:11], v[22:23] op_sel_hi:[1,0]
	v_pk_mul_f32 v[8:9], v[8:9], v[22:23] op_sel_hi:[1,0]
	v_pk_mul_f32 v[6:7], v[6:7], v[22:23] op_sel_hi:[1,0]
	v_pk_mul_f32 v[4:5], v[4:5], v[22:23] op_sel_hi:[1,0]
	v_pk_mul_f32 v[2:3], v[2:3], v[22:23] op_sel_hi:[1,0]
	v_pk_mul_f32 v[0:1], v[0:1], v[22:23] op_sel_hi:[1,0]
	s_waitcnt lgkmcnt(0)
	v_pk_mul_f32 v[8:9], v[12:13], v[8:9]
	v_pk_mul_f32 v[10:11], v[14:15], v[10:11]
	global_store_dwordx4 v[16:17], v[8:11], off offset:16
	ds_read_b128 v[8:11], v238 offset:512
	s_waitcnt lgkmcnt(0)
	v_pk_mul_f32 v[4:5], v[8:9], v[4:5]
	v_pk_mul_f32 v[6:7], v[10:11], v[6:7]
	global_store_dwordx4 v[16:17], v[4:7], off offset:512
	ds_read_b128 v[4:7], v238 offset:528
	s_waitcnt lgkmcnt(0)
	v_pk_mul_f32 v[0:1], v[0:1], v[4:5]
	v_pk_mul_f32 v[2:3], v[2:3], v[6:7]
	global_store_dwordx4 v[16:17], v[0:3], off offset:528
	s_cbranch_vccnz .LBB0_2184
	s_andn2_b64 vcc, exec, s[2:3]
	s_cbranch_vccnz .LBB0_2183
	s_barrier
	s_branch .LBB0_2183
